# P1 fast-path epilogues: all tiles use plain write-back stores (P2.5 keeps write-through on its last tile only)
# speedup vs baseline: 1.0148x; 1.0024x over previous
.LBB0_135:
	s_ashr_i32 s73, s46, 1
	s_and_b32 s71, s46, 1
	s_cmp_lt_u32 s8, 6
	s_cbranch_scc0 .Lp1_late
	s_cmp_lt_u32 s46, 4
	s_cbranch_scc1 .Lepi_plain_e
	s_cmp_eq_u32 s73, 4
	s_cbranch_scc1 .Lepi_plain_e
	s_cmp_eq_u32 s73, 6
	s_cbranch_scc1 .Lepi_gelu_e
	s_cmp_eq_u32 s73, 7
	s_cbranch_scc1 .Lepi_gelu_e
	s_cmp_lg_u32 s73, 2
	s_cbranch_scc1 .Lepi_silu_e
